# strategy 7 (address arithmetic into offset:N immediates): HGRN stage C q-column prefetch uses 4 base pointers with immediate offsets instead of 16 separate 64-bit address chains
# speedup vs baseline: 1.0049x; 1.0019x over previous
; DI float bf2f(bf16_t v) { return __uint_as_float(((unsigned)v) << 16); }
; DI void hgrn_stageC(const Params& p, const int j_even, char* lds) {
;     ...
;   if (blockIdx.x < 2048) HC_FETCH(blockIdx.x);
;   for (int task = blockIdx.x; task < 2048; task += gridDim.x) {
;     const int bh = task >> 8, c = task & 255, b = bh >> 2, h = bh & 3;
;     const int tok0 = b * SEQ + c * 64;
; #pragma unroll
;     for (int i = 0; i < 4; ++i) { const int idx = tid + 512 * i, row = idx >> 5, c4 = idx & 31; *(f32x4*)(lfT + row * 128 + c4 * 4) = lfr[i]; }
; #pragma unroll
;     for (int i = 0; i < 2; ++i) { const int idx = tid + 512 * i, row = idx >> 3, ch = idx & 7; *(u32x4*)(IT + row * LROW + ch * 16) = itr[i]; }
;     float qcur[16];
; #pragma unroll
;     for (int i = 0; i < 16; ++i) qcur[i] = bf2f(qr[i]);
;     u32x4 sreg[4];
; #pragma unroll
;     for (int i = 0; i < 4; ++i) sreg[i] = *(const u32x4*)(UT + (size_t)task * 16384 + (size_t)(tid + 512 * i) * 8);
;     if (task + (int)gridDim.x < 2048) HC_FETCH(task + (int)gridDim.x);
.LBB0_593:
	s_ashr_i32 s5, s4, 31
	s_lshl_b64 s[2:3], s[4:5], 15
	s_add_u32 s2, s22, s2
	s_addc_u32 s3, s23, s3
	v_lshl_add_u64 v[2:3], s[2:3], 0, v[144:145]
	v_lshl_add_u64 v[6:7], s[2:3], 0, v[146:147]
	v_lshl_add_u64 v[10:11], s[2:3], 0, v[148:149]
	v_lshl_add_u64 v[14:15], s[2:3], 0, v[150:151]
	global_load_dwordx4 v[2:5], v[2:3], off
	s_nop 0
	global_load_dwordx4 v[6:9], v[6:7], off
	s_nop 0
	global_load_dwordx4 v[10:13], v[10:11], off
	s_nop 0
	global_load_dwordx4 v[14:17], v[14:15], off
	s_add_i32 s2, s4, s24
	s_cmpk_gt_i32 s2, 0x7ff
	s_cselect_b64 s[88:89], -1, 0
	s_and_b64 vcc, exec, s[88:89]
	ds_write_b128 v169, v[112:115]
	ds_write_b128 v169, v[116:119] offset:8192
	ds_write_b128 v169, v[120:123] offset:16384
	ds_write_b128 v169, v[124:127] offset:24576
	ds_write_b128 v170, v[128:131]
	ds_write_b128 v171, v[132:135]
	s_cbranch_vccnz .LBB0_595
	s_add_i32 s3, s25, s28
	s_add_i32 s5, s26, s27
	s_and_b32 s3, s3, 0xffffc000
	s_and_b32 s5, s5, 0x3fc0
	s_or_b32 s3, s3, s5
	s_ashr_i32 s29, s2, 1
	s_and_b32 s30, s29, 0xffffff80
	s_and_b32 s29, s29, 0x180
	v_add_u32_e32 v36, s3, v156
	s_lshl_b32 s96, s29, 2
	v_ashrrev_i32_e32 v37, 31, v36
	v_lshl_add_u64 v[34:35], v[136:137], 0, s[96:97]
	v_lshlrev_b64 v[36:37], 11, v[36:37]
	v_lshl_add_u64 v[36:37], v[34:35], 0, v[36:37]
	global_load_dwordx4 v[112:115], v[36:37], off
	v_add_u32_e32 v36, s3, v158
	v_ashrrev_i32_e32 v37, 31, v36
	v_lshlrev_b64 v[36:37], 11, v[36:37]
	v_lshl_add_u64 v[36:37], v[34:35], 0, v[36:37]
	global_load_dwordx4 v[116:119], v[36:37], off
	v_add_u32_e32 v36, s3, v159
	v_ashrrev_i32_e32 v37, 31, v36
	v_lshlrev_b64 v[36:37], 11, v[36:37]
	v_lshl_add_u64 v[36:37], v[34:35], 0, v[36:37]
	global_load_dwordx4 v[120:123], v[36:37], off
	v_add_u32_e32 v36, s3, v160
	v_ashrrev_i32_e32 v37, 31, v36
	v_lshlrev_b64 v[36:37], 11, v[36:37]
	v_lshl_add_u64 v[34:35], v[34:35], 0, v[36:37]
	v_add_u32_e32 v36, s30, v157
	s_lshl_b32 s96, s5, 1
	v_ashrrev_i32_e32 v37, 31, v36
	global_load_dwordx4 v[124:127], v[34:35], off
	v_lshl_add_u64 v[34:35], v[138:139], 0, s[96:97]
	v_lshlrev_b64 v[36:37], 15, v[36:37]
	v_lshl_add_u64 v[36:37], v[34:35], 0, v[36:37]
	global_load_dwordx4 v[128:131], v[36:37], off
	v_add_u32_e32 v36, s30, v161
	v_ashrrev_i32_e32 v37, 31, v36
	v_lshlrev_b64 v[36:37], 15, v[36:37]
	v_lshl_add_u64 v[34:35], v[34:35], 0, v[36:37]
	global_load_dwordx4 v[132:135], v[34:35], off
	v_add_u32_e32 v34, s3, v162
	s_lshl_b32 s96, s29, 1
	v_ashrrev_i32_e32 v35, 31, v34
	v_lshl_add_u64 v[36:37], v[140:141], 0, s[96:97]
	v_lshlrev_b64 v[38:39], 10, v[34:35]
	v_lshl_add_u64 v[38:39], v[36:37], 0, v[38:39]
	s_movk_i32 s96, 0x1000
	v_lshl_add_u64 v[70:71], v[38:39], 0, s[96:97]
	v_lshl_add_u64 v[72:73], v[70:71], 0, s[96:97]
	v_lshl_add_u64 v[74:75], v[72:73], 0, s[96:97]
	global_load_ushort v182, v[38:39], off
	global_load_ushort v183, v[38:39], off offset:1024
	global_load_ushort v184, v[38:39], off offset:2048
	global_load_ushort v185, v[38:39], off offset:3072
	global_load_ushort v186, v[70:71], off
	global_load_ushort v187, v[70:71], off offset:1024
	global_load_ushort v188, v[70:71], off offset:2048
	global_load_ushort v189, v[70:71], off offset:3072
	global_load_ushort v190, v[72:73], off
	global_load_ushort v191, v[72:73], off offset:1024
	global_load_ushort v208, v[72:73], off offset:2048
	global_load_ushort v209, v[72:73], off offset:3072
	global_load_ushort v210, v[74:75], off
	global_load_ushort v211, v[74:75], off offset:1024
	global_load_ushort v212, v[74:75], off offset:2048
	global_load_ushort v213, v[74:75], off offset:3072
